# GEMM phases: accumulator re-zeroing before each tile with 64 v_mov_b64 instead of 128 v_mov_b32 (6 phases)
# baseline (speedup 1.0000x reference)
; template <class Epi>
; DI void gemm_phase(PG8_LAS unsigned char* lds, const Gemm g, const StaticOrder& S, const Epi& E) {
;     ...
;         const bool has_next = S.next(ui + 1, nxt);
;         const char* nA = has_next ? (const char*)g.A + (size_t)nxt.pm * tstepA + (size_t)nxt.pn * g.a_pn_off : cA; const char* nB = has_next ? (const char*)g.Bt + (size_t)nxt.pn * tstepB : cB;
;     ...
; #pragma unroll
;         for (int a = 0; a < 2; ++a)
; #pragma unroll
;             for (int b = 0; b < 2; ++b)
; #pragma unroll
;                 for (int m = 0; m < 4; ++m)
; #pragma unroll
;                     for (int n = 0; n < 2; ++n) acc[a][b][m][n] = (f32x4){0.f, 0.f, 0.f, 0.f};
.LBB0_282:
	s_ashr_i32 s17, s16, 31
	s_lshl_b64 s[22:23], s[16:17], 19
	s_add_u32 s22, s94, s22
	s_addc_u32 s23, s95, s23
	s_and_b64 s[24:25], s[0:1], exec
	s_cselect_b32 s6, s23, s29
	s_cselect_b32 s17, s22, s28
	s_ashr_i32 s15, s14, 31
	s_lshl_b64 s[24:25], s[14:15], 19
	s_add_u32 s24, s70, s24
	s_addc_u32 s25, s71, s25
	s_and_b64 s[34:35], s[0:1], exec
	s_cselect_b32 s15, s25, s31
	s_cselect_b32 s50, s24, s30
	s_add_u32 s28, s28, 0x40080
	s_addc_u32 s29, s29, 0
	s_add_u32 s51, s30, 0x100
	v_mov_b64_e32 v[0:1], 0
	s_addc_u32 s52, s31, 0
	s_mov_b32 s53, -2
	v_mov_b64_e32 v[2:3], 0
	v_mov_b64_e32 v[4:5], 0
	v_mov_b64_e32 v[6:7], 0
	v_mov_b64_e32 v[16:17], 0
	v_mov_b64_e32 v[18:19], 0
	v_mov_b64_e32 v[20:21], 0
	v_mov_b64_e32 v[22:23], 0
	v_mov_b64_e32 v[32:33], 0
	v_mov_b64_e32 v[34:35], 0
	v_mov_b64_e32 v[36:37], 0
	v_mov_b64_e32 v[38:39], 0
	v_mov_b64_e32 v[48:49], 0
	v_mov_b64_e32 v[50:51], 0
	v_mov_b64_e32 v[52:53], 0
	v_mov_b64_e32 v[54:55], 0
	v_mov_b64_e32 v[8:9], 0
	v_mov_b64_e32 v[10:11], 0
	v_mov_b64_e32 v[12:13], 0
	v_mov_b64_e32 v[14:15], 0
	v_mov_b64_e32 v[24:25], 0
	v_mov_b64_e32 v[26:27], 0
	v_mov_b64_e32 v[28:29], 0
	v_mov_b64_e32 v[30:31], 0
	v_mov_b64_e32 v[40:41], 0
	v_mov_b64_e32 v[42:43], 0
	v_mov_b64_e32 v[44:45], 0
	v_mov_b64_e32 v[46:47], 0
	v_mov_b64_e32 v[56:57], 0
	v_mov_b64_e32 v[58:59], 0
	v_mov_b64_e32 v[60:61], 0
	v_mov_b64_e32 v[62:63], 0
	v_mov_b64_e32 v[64:65], 0
	v_mov_b64_e32 v[66:67], 0
	v_mov_b64_e32 v[68:69], 0
	v_mov_b64_e32 v[70:71], 0
	v_mov_b64_e32 v[80:81], 0
	v_mov_b64_e32 v[82:83], 0
	v_mov_b64_e32 v[84:85], 0
	v_mov_b64_e32 v[86:87], 0
	v_mov_b64_e32 v[104:105], 0
	v_mov_b64_e32 v[106:107], 0
	v_mov_b64_e32 v[108:109], 0
	v_mov_b64_e32 v[110:111], 0
	v_mov_b64_e32 v[128:129], 0
	v_mov_b64_e32 v[130:131], 0
	v_mov_b64_e32 v[132:133], 0
	v_mov_b64_e32 v[134:135], 0
	v_mov_b64_e32 v[72:73], 0
	v_mov_b64_e32 v[74:75], 0
	v_mov_b64_e32 v[76:77], 0
	v_mov_b64_e32 v[78:79], 0
	v_mov_b64_e32 v[88:89], 0
	v_mov_b64_e32 v[90:91], 0
	v_mov_b64_e32 v[100:101], 0
	v_mov_b64_e32 v[102:103], 0
	v_mov_b64_e32 v[120:121], 0
	v_mov_b64_e32 v[122:123], 0
	v_mov_b64_e32 v[124:125], 0
	v_mov_b64_e32 v[126:127], 0
	v_mov_b64_e32 v[136:137], 0
	v_mov_b64_e32 v[138:139], 0
	v_mov_b64_e32 v[140:141], 0
	v_mov_b64_e32 v[142:143], 0

; template <class Epi>
; DI void gemm_phase(PG8_LAS unsigned char* lds, const Gemm g, const StaticOrder& S, const Epi& E) {
;     ...
;         const bool has_next = S.next(ui + 1, nxt);
;         const char* nA = has_next ? (const char*)g.A + (size_t)nxt.pm * tstepA + (size_t)nxt.pn * g.a_pn_off : cA; const char* nB = has_next ? (const char*)g.Bt + (size_t)nxt.pn * tstepB : cB;
;     ...
; #pragma unroll
;         for (int a = 0; a < 2; ++a)
; #pragma unroll
;             for (int b = 0; b < 2; ++b)
; #pragma unroll
;                 for (int m = 0; m < 4; ++m)
; #pragma unroll
;                     for (int n = 0; n < 2; ++n) acc[a][b][m][n] = (f32x4){0.f, 0.f, 0.f, 0.f};
.LBB0_654:
	s_ashr_i32 s13, s12, 31
	s_lshl_b64 s[14:15], s[12:13], 18
	s_add_u32 s14, s68, s14
	s_addc_u32 s15, s69, s15
	s_and_b64 s[16:17], s[0:1], exec
	s_cselect_b32 s13, s15, s25
	s_cselect_b32 s47, s14, s24
	s_ashr_i32 s11, s10, 31
	s_lshl_b64 s[16:17], s[10:11], 18
	s_add_u32 s16, s30, s16
	s_addc_u32 s17, s31, s17
	s_and_b64 s[28:29], s[0:1], exec
	s_cselect_b32 s11, s17, s27
	s_cselect_b32 s48, s16, s26
	s_add_u32 s24, s24, 0x20080
	s_addc_u32 s25, s25, 0
	s_add_u32 s49, s26, 0x100
	v_mov_b64_e32 v[4:5], 0
	s_addc_u32 s50, s27, 0
	s_mov_b32 s51, -2
	v_mov_b64_e32 v[6:7], 0
	v_mov_b64_e32 v[0:1], 0
	v_mov_b64_e32 v[2:3], 0
	v_mov_b64_e32 v[20:21], 0
	v_mov_b64_e32 v[22:23], 0
	v_mov_b64_e32 v[16:17], 0
	v_mov_b64_e32 v[18:19], 0
	v_mov_b64_e32 v[36:37], 0
	v_mov_b64_e32 v[38:39], 0
	v_mov_b64_e32 v[32:33], 0
	v_mov_b64_e32 v[34:35], 0
	v_mov_b64_e32 v[52:53], 0
	v_mov_b64_e32 v[54:55], 0
	v_mov_b64_e32 v[48:49], 0
	v_mov_b64_e32 v[50:51], 0
	v_mov_b64_e32 v[12:13], 0
	v_mov_b64_e32 v[14:15], 0
	v_mov_b64_e32 v[8:9], 0
	v_mov_b64_e32 v[10:11], 0
	v_mov_b64_e32 v[28:29], 0
	v_mov_b64_e32 v[30:31], 0
	v_mov_b64_e32 v[24:25], 0
	v_mov_b64_e32 v[26:27], 0
	v_mov_b64_e32 v[44:45], 0
	v_mov_b64_e32 v[46:47], 0
	v_mov_b64_e32 v[40:41], 0
	v_mov_b64_e32 v[42:43], 0
	v_mov_b64_e32 v[60:61], 0
	v_mov_b64_e32 v[62:63], 0
	v_mov_b64_e32 v[56:57], 0
	v_mov_b64_e32 v[58:59], 0
	v_mov_b64_e32 v[68:69], 0
	v_mov_b64_e32 v[70:71], 0
	v_mov_b64_e32 v[64:65], 0
	v_mov_b64_e32 v[66:67], 0
	v_mov_b64_e32 v[84:85], 0
	v_mov_b64_e32 v[86:87], 0
	v_mov_b64_e32 v[80:81], 0
	v_mov_b64_e32 v[82:83], 0
	v_mov_b64_e32 v[100:101], 0
	v_mov_b64_e32 v[102:103], 0
	v_mov_b64_e32 v[96:97], 0
	v_mov_b64_e32 v[98:99], 0
	v_mov_b64_e32 v[116:117], 0
	v_mov_b64_e32 v[118:119], 0
	v_mov_b64_e32 v[112:113], 0
	v_mov_b64_e32 v[114:115], 0
	v_mov_b64_e32 v[76:77], 0
	v_mov_b64_e32 v[78:79], 0
	v_mov_b64_e32 v[72:73], 0
	v_mov_b64_e32 v[74:75], 0
	v_mov_b64_e32 v[92:93], 0
	v_mov_b64_e32 v[94:95], 0
	v_mov_b64_e32 v[88:89], 0
	v_mov_b64_e32 v[90:91], 0
	v_mov_b64_e32 v[108:109], 0
	v_mov_b64_e32 v[110:111], 0
	v_mov_b64_e32 v[104:105], 0
	v_mov_b64_e32 v[106:107], 0
	v_mov_b64_e32 v[124:125], 0
	v_mov_b64_e32 v[126:127], 0
	v_mov_b64_e32 v[120:121], 0
	v_mov_b64_e32 v[122:123], 0

; template <class Epi>
; DI void gemm_phase(PG8_LAS unsigned char* lds, const Gemm g, const StaticOrder& S, const Epi& E) {
;     ...
;         const bool has_next = S.next(ui + 1, nxt);
;         const char* nA = has_next ? (const char*)g.A + (size_t)nxt.pm * tstepA + (size_t)nxt.pn * g.a_pn_off : cA; const char* nB = has_next ? (const char*)g.Bt + (size_t)nxt.pn * tstepB : cB;
;     ...
; #pragma unroll
;         for (int a = 0; a < 2; ++a)
; #pragma unroll
;             for (int b = 0; b < 2; ++b)
; #pragma unroll
;                 for (int m = 0; m < 4; ++m)
; #pragma unroll
;                     for (int n = 0; n < 2; ++n) acc[a][b][m][n] = (f32x4){0.f, 0.f, 0.f, 0.f};
.LBB0_851:
	s_ashr_i32 s21, s20, 31
	s_lshl_b64 s[22:23], s[20:21], 19
	s_add_u32 s22, s68, s22
	s_addc_u32 s23, s69, s23
	s_and_b64 s[24:25], s[4:5], exec
	s_cselect_b32 s21, s23, s29
	s_cselect_b32 s85, s22, s28
	s_ashr_i32 s19, s18, 31
	s_lshl_b64 s[24:25], s[18:19], 19
	s_add_u32 s24, s36, s24
	s_addc_u32 s25, s37, s25
	s_and_b64 s[34:35], s[4:5], exec
	s_cselect_b32 s19, s25, s31
	s_cselect_b32 s86, s24, s30
	s_add_u32 s28, s28, 0x40080
	s_addc_u32 s29, s29, 0
	s_add_u32 s87, s30, 0x100
	v_mov_b64_e32 v[0:1], 0
	s_addc_u32 s90, s31, 0
	s_mov_b32 s91, -2
	v_mov_b64_e32 v[2:3], 0
	v_mov_b64_e32 v[4:5], 0
	v_mov_b64_e32 v[6:7], 0
	v_mov_b64_e32 v[16:17], 0
	v_mov_b64_e32 v[18:19], 0
	v_mov_b64_e32 v[20:21], 0
	v_mov_b64_e32 v[22:23], 0
	v_mov_b64_e32 v[32:33], 0
	v_mov_b64_e32 v[34:35], 0
	v_mov_b64_e32 v[36:37], 0
	v_mov_b64_e32 v[38:39], 0
	v_mov_b64_e32 v[48:49], 0
	v_mov_b64_e32 v[50:51], 0
	v_mov_b64_e32 v[52:53], 0
	v_mov_b64_e32 v[54:55], 0
	v_mov_b64_e32 v[8:9], 0
	v_mov_b64_e32 v[10:11], 0
	v_mov_b64_e32 v[12:13], 0
	v_mov_b64_e32 v[14:15], 0
	v_mov_b64_e32 v[24:25], 0
	v_mov_b64_e32 v[26:27], 0
	v_mov_b64_e32 v[28:29], 0
	v_mov_b64_e32 v[30:31], 0
	v_mov_b64_e32 v[40:41], 0
	v_mov_b64_e32 v[42:43], 0
	v_mov_b64_e32 v[44:45], 0
	v_mov_b64_e32 v[46:47], 0
	v_mov_b64_e32 v[56:57], 0
	v_mov_b64_e32 v[58:59], 0
	v_mov_b64_e32 v[60:61], 0
	v_mov_b64_e32 v[62:63], 0
	v_mov_b64_e32 v[64:65], 0
	v_mov_b64_e32 v[66:67], 0
	v_mov_b64_e32 v[68:69], 0
	v_mov_b64_e32 v[70:71], 0
	v_mov_b64_e32 v[80:81], 0
	v_mov_b64_e32 v[82:83], 0
	v_mov_b64_e32 v[84:85], 0
	v_mov_b64_e32 v[86:87], 0
	v_mov_b64_e32 v[96:97], 0
	v_mov_b64_e32 v[98:99], 0
	v_mov_b64_e32 v[100:101], 0
	v_mov_b64_e32 v[102:103], 0
	v_mov_b64_e32 v[112:113], 0
	v_mov_b64_e32 v[114:115], 0
	v_mov_b64_e32 v[116:117], 0
	v_mov_b64_e32 v[118:119], 0
	v_mov_b64_e32 v[72:73], 0
	v_mov_b64_e32 v[74:75], 0
	v_mov_b64_e32 v[76:77], 0
	v_mov_b64_e32 v[78:79], 0
	v_mov_b64_e32 v[88:89], 0
	v_mov_b64_e32 v[90:91], 0
	v_mov_b64_e32 v[92:93], 0
	v_mov_b64_e32 v[94:95], 0
	v_mov_b64_e32 v[104:105], 0
	v_mov_b64_e32 v[106:107], 0
	v_mov_b64_e32 v[108:109], 0
	v_mov_b64_e32 v[110:111], 0
	v_mov_b64_e32 v[120:121], 0
	v_mov_b64_e32 v[122:123], 0
	v_mov_b64_e32 v[124:125], 0
	v_mov_b64_e32 v[126:127], 0

; template <class Epi>
; DI void gemm_phase(PG8_LAS unsigned char* lds, const Gemm g, const StaticOrder& S, const Epi& E) {
;     ...
;         const bool has_next = S.next(ui + 1, nxt);
;         const char* nA = has_next ? (const char*)g.A + (size_t)nxt.pm * tstepA + (size_t)nxt.pn * g.a_pn_off : cA; const char* nB = has_next ? (const char*)g.Bt + (size_t)nxt.pn * tstepB : cB;
;     ...
; #pragma unroll
;         for (int a = 0; a < 2; ++a)
; #pragma unroll
;             for (int b = 0; b < 2; ++b)
; #pragma unroll
;                 for (int m = 0; m < 4; ++m)
; #pragma unroll
;                     for (int n = 0; n < 2; ++n) acc[a][b][m][n] = (f32x4){0.f, 0.f, 0.f, 0.f};
.LBB0_927:
	s_ashr_i32 s29, s28, 31
	s_lshl_b64 s[30:31], s[28:29], 19
	s_add_u32 s30, s96, s30
	s_addc_u32 s31, s97, s31
	s_and_b64 s[34:35], s[4:5], exec
	s_cselect_b32 s29, s31, s39
	s_cselect_b32 s85, s30, s38
	s_ashr_i32 s27, s26, 31
	s_lshl_b64 s[34:35], s[26:27], 19
	s_add_u32 s34, s15, s34
	s_addc_u32 s35, s44, s35
	s_and_b64 s[42:43], s[4:5], exec
	s_cselect_b32 s27, s35, s41
	s_cselect_b32 s86, s34, s40
	s_add_u32 s38, s38, 0x40080
	s_addc_u32 s39, s39, 0
	s_add_u32 s87, s40, 0x100
	v_mov_b64_e32 v[0:1], 0
	s_addc_u32 s90, s41, 0
	s_mov_b32 s91, -2
	v_mov_b64_e32 v[2:3], 0
	v_mov_b64_e32 v[4:5], 0
	v_mov_b64_e32 v[6:7], 0
	v_mov_b64_e32 v[16:17], 0
	v_mov_b64_e32 v[18:19], 0
	v_mov_b64_e32 v[20:21], 0
	v_mov_b64_e32 v[22:23], 0
	v_mov_b64_e32 v[32:33], 0
	v_mov_b64_e32 v[34:35], 0
	v_mov_b64_e32 v[36:37], 0
	v_mov_b64_e32 v[38:39], 0
	v_mov_b64_e32 v[48:49], 0
	v_mov_b64_e32 v[50:51], 0
	v_mov_b64_e32 v[52:53], 0
	v_mov_b64_e32 v[54:55], 0
	v_mov_b64_e32 v[8:9], 0
	v_mov_b64_e32 v[10:11], 0
	v_mov_b64_e32 v[12:13], 0
	v_mov_b64_e32 v[14:15], 0
	v_mov_b64_e32 v[24:25], 0
	v_mov_b64_e32 v[26:27], 0
	v_mov_b64_e32 v[28:29], 0
	v_mov_b64_e32 v[30:31], 0
	v_mov_b64_e32 v[40:41], 0
	v_mov_b64_e32 v[42:43], 0
	v_mov_b64_e32 v[44:45], 0
	v_mov_b64_e32 v[46:47], 0
	v_mov_b64_e32 v[56:57], 0
	v_mov_b64_e32 v[58:59], 0
	v_mov_b64_e32 v[60:61], 0
	v_mov_b64_e32 v[62:63], 0
	v_mov_b64_e32 v[64:65], 0
	v_mov_b64_e32 v[66:67], 0
	v_mov_b64_e32 v[68:69], 0
	v_mov_b64_e32 v[70:71], 0
	v_mov_b64_e32 v[80:81], 0
	v_mov_b64_e32 v[82:83], 0
	v_mov_b64_e32 v[84:85], 0
	v_mov_b64_e32 v[86:87], 0
	v_mov_b64_e32 v[96:97], 0
	v_mov_b64_e32 v[98:99], 0
	v_mov_b64_e32 v[100:101], 0
	v_mov_b64_e32 v[102:103], 0
	v_mov_b64_e32 v[112:113], 0
	v_mov_b64_e32 v[114:115], 0
	v_mov_b64_e32 v[116:117], 0
	v_mov_b64_e32 v[118:119], 0
	v_mov_b64_e32 v[72:73], 0
	v_mov_b64_e32 v[74:75], 0
	v_mov_b64_e32 v[76:77], 0
	v_mov_b64_e32 v[78:79], 0
	v_mov_b64_e32 v[88:89], 0
	v_mov_b64_e32 v[90:91], 0
	v_mov_b64_e32 v[92:93], 0
	v_mov_b64_e32 v[94:95], 0
	v_mov_b64_e32 v[104:105], 0
	v_mov_b64_e32 v[106:107], 0
	v_mov_b64_e32 v[108:109], 0
	v_mov_b64_e32 v[110:111], 0
	v_mov_b64_e32 v[120:121], 0
	v_mov_b64_e32 v[122:123], 0
	v_mov_b64_e32 v[124:125], 0
	v_mov_b64_e32 v[126:127], 0

; template <class Epi>
; DI void gemm_phase(PG8_LAS unsigned char* lds, const Gemm g, const StaticOrder& S, const Epi& E) {
;     ...
;         const bool has_next = S.next(ui + 1, nxt);
;         const char* nA = has_next ? (const char*)g.A + (size_t)nxt.pm * tstepA + (size_t)nxt.pn * g.a_pn_off : cA; const char* nB = has_next ? (const char*)g.Bt + (size_t)nxt.pn * tstepB : cB;
;     ...
; #pragma unroll
;         for (int a = 0; a < 2; ++a)
; #pragma unroll
;             for (int b = 0; b < 2; ++b)
; #pragma unroll
;                 for (int m = 0; m < 4; ++m)
; #pragma unroll
;                     for (int n = 0; n < 2; ++n) acc[a][b][m][n] = (f32x4){0.f, 0.f, 0.f, 0.f};
.LBB0_1060:
	s_ashr_i32 s29, s28, 31
	s_lshl_b64 s[30:31], s[28:29], 19
	s_add_u32 s30, s96, s30
	s_addc_u32 s31, s97, s31
	s_and_b64 s[34:35], s[8:9], exec
	s_cselect_b32 s5, s31, s37
	s_cselect_b32 s7, s30, s36
	s_ashr_i32 s27, s26, 31
	s_lshl_b64 s[34:35], s[26:27], 19
	s_add_u32 s34, s3, s34
	s_addc_u32 s35, s42, s35
	s_and_b64 s[40:41], s[8:9], exec
	s_cselect_b32 s27, s35, s39
	s_cselect_b32 s29, s34, s38
	s_add_u32 s36, s36, 0x40080
	s_addc_u32 s37, s37, 0
	s_add_u32 s78, s38, 0x100
	v_mov_b64_e32 v[0:1], 0
	s_addc_u32 s79, s39, 0
	s_mov_b32 s80, -2
	v_mov_b64_e32 v[2:3], 0
	v_mov_b64_e32 v[4:5], 0
	v_mov_b64_e32 v[6:7], 0
	v_mov_b64_e32 v[8:9], 0
	v_mov_b64_e32 v[10:11], 0
	v_mov_b64_e32 v[12:13], 0
	v_mov_b64_e32 v[14:15], 0
	v_mov_b64_e32 v[16:17], 0
	v_mov_b64_e32 v[18:19], 0
	v_mov_b64_e32 v[20:21], 0
	v_mov_b64_e32 v[22:23], 0
	v_mov_b64_e32 v[24:25], 0
	v_mov_b64_e32 v[26:27], 0
	v_mov_b64_e32 v[28:29], 0
	v_mov_b64_e32 v[30:31], 0
	v_mov_b64_e32 v[80:81], 0
	v_mov_b64_e32 v[82:83], 0
	v_mov_b64_e32 v[84:85], 0
	v_mov_b64_e32 v[86:87], 0
	v_mov_b64_e32 v[88:89], 0
	v_mov_b64_e32 v[90:91], 0
	v_mov_b64_e32 v[92:93], 0
	v_mov_b64_e32 v[94:95], 0
	v_mov_b64_e32 v[96:97], 0
	v_mov_b64_e32 v[98:99], 0
	v_mov_b64_e32 v[100:101], 0
	v_mov_b64_e32 v[102:103], 0
	v_mov_b64_e32 v[104:105], 0
	v_mov_b64_e32 v[106:107], 0
	v_mov_b64_e32 v[108:109], 0
	v_mov_b64_e32 v[110:111], 0
	v_mov_b64_e32 v[32:33], 0
	v_mov_b64_e32 v[34:35], 0
	v_mov_b64_e32 v[36:37], 0
	v_mov_b64_e32 v[38:39], 0
	v_mov_b64_e32 v[40:41], 0
	v_mov_b64_e32 v[42:43], 0
	v_mov_b64_e32 v[44:45], 0
	v_mov_b64_e32 v[46:47], 0
	v_mov_b64_e32 v[48:49], 0
	v_mov_b64_e32 v[50:51], 0
	v_mov_b64_e32 v[52:53], 0
	v_mov_b64_e32 v[54:55], 0
	v_mov_b64_e32 v[56:57], 0
	v_mov_b64_e32 v[58:59], 0
	v_mov_b64_e32 v[60:61], 0
	v_mov_b64_e32 v[62:63], 0
	v_mov_b64_e32 v[112:113], 0
	v_mov_b64_e32 v[114:115], 0
	v_mov_b64_e32 v[116:117], 0
	v_mov_b64_e32 v[118:119], 0
	v_mov_b64_e32 v[120:121], 0
	v_mov_b64_e32 v[122:123], 0
	v_mov_b64_e32 v[124:125], 0
	v_mov_b64_e32 v[126:127], 0
	v_mov_b64_e32 v[128:129], 0
	v_mov_b64_e32 v[130:131], 0
	v_mov_b64_e32 v[132:133], 0
	v_mov_b64_e32 v[134:135], 0
	v_mov_b64_e32 v[136:137], 0
	v_mov_b64_e32 v[138:139], 0
	v_mov_b64_e32 v[152:153], 0
	v_mov_b64_e32 v[154:155], 0

; template <class Epi>
; DI void gemm_phase(PG8_LAS unsigned char* lds, const Gemm g, const StaticOrder& S, const Epi& E) {
;     ...
; #pragma unroll
;         for (int a = 0; a < 2; ++a)
; #pragma unroll
;             for (int b = 0; b < 2; ++b)
; #pragma unroll
;                 for (int m = 0; m < 4; ++m)
; #pragma unroll
;                     for (int n = 0; n < 2; ++n) acc[a][b][m][n] = (f32x4){0.f, 0.f, 0.f, 0.f};
.LBB0_1223:
	s_add_u32 s55, s22, 0x100
	v_mov_b64_e32 v[0:1], 0
	s_addc_u32 s56, s23, 0
	s_mov_b32 s57, -2
	v_mov_b64_e32 v[2:3], 0
	v_mov_b64_e32 v[4:5], 0
	v_mov_b64_e32 v[6:7], 0
	v_mov_b64_e32 v[16:17], 0
	v_mov_b64_e32 v[18:19], 0
	v_mov_b64_e32 v[20:21], 0
	v_mov_b64_e32 v[22:23], 0
	v_mov_b64_e32 v[28:29], 0
	v_mov_b64_e32 v[30:31], 0
	v_mov_b64_e32 v[36:37], 0
	v_mov_b64_e32 v[38:39], 0
	v_mov_b64_e32 v[48:49], 0
	v_mov_b64_e32 v[50:51], 0
	v_mov_b64_e32 v[52:53], 0
	v_mov_b64_e32 v[54:55], 0
	v_mov_b64_e32 v[8:9], 0
	v_mov_b64_e32 v[10:11], 0
	v_mov_b64_e32 v[12:13], 0
	v_mov_b64_e32 v[14:15], 0
	v_mov_b64_e32 v[24:25], 0
	v_mov_b64_e32 v[26:27], 0
	v_mov_b64_e32 v[32:33], 0
	v_mov_b64_e32 v[34:35], 0
	v_mov_b64_e32 v[40:41], 0
	v_mov_b64_e32 v[42:43], 0
	v_mov_b64_e32 v[44:45], 0
	v_mov_b64_e32 v[46:47], 0
	v_mov_b64_e32 v[56:57], 0
	v_mov_b64_e32 v[58:59], 0
	v_mov_b64_e32 v[60:61], 0
	v_mov_b64_e32 v[62:63], 0
	v_mov_b64_e32 v[64:65], 0
	v_mov_b64_e32 v[66:67], 0
	v_mov_b64_e32 v[68:69], 0
	v_mov_b64_e32 v[70:71], 0
	v_mov_b64_e32 v[80:81], 0
	v_mov_b64_e32 v[82:83], 0
	v_mov_b64_e32 v[84:85], 0
	v_mov_b64_e32 v[86:87], 0
	v_mov_b64_e32 v[96:97], 0
	v_mov_b64_e32 v[98:99], 0
	v_mov_b64_e32 v[100:101], 0
	v_mov_b64_e32 v[102:103], 0
	v_mov_b64_e32 v[112:113], 0
	v_mov_b64_e32 v[114:115], 0
	v_mov_b64_e32 v[116:117], 0
	v_mov_b64_e32 v[118:119], 0
	v_mov_b64_e32 v[72:73], 0
	v_mov_b64_e32 v[74:75], 0
	v_mov_b64_e32 v[76:77], 0
	v_mov_b64_e32 v[78:79], 0
	v_mov_b64_e32 v[88:89], 0
	v_mov_b64_e32 v[90:91], 0
	v_mov_b64_e32 v[92:93], 0
	v_mov_b64_e32 v[94:95], 0
	v_mov_b64_e32 v[104:105], 0
	v_mov_b64_e32 v[106:107], 0
	v_mov_b64_e32 v[108:109], 0
	v_mov_b64_e32 v[110:111], 0
	v_mov_b64_e32 v[120:121], 0
	v_mov_b64_e32 v[122:123], 0
	v_mov_b64_e32 v[124:125], 0
	v_mov_b64_e32 v[126:127], 0
